# stack: v12 + EpiRes epilogue (gates once per tile, x ring) + band-attn LDS read batching + NORM loads hoisted
# speedup vs baseline: 1.0139x; 1.0139x over previous
; #define LAS __attribute__((address_space(3)))
; template <int HD, int DV, int HW, int MODE> ...
;     ...
; #pragma unroll
;             for (int i = 0; i < 16; ++i) S[i] = __builtin_amdgcn_exp2f(S[i] - m);
;             l += sum16(S);
;             const bf16x8 P0 = pack8(S, 0), P1 = pack8(S, 8);
; #pragma unroll
;             for (int t = 0; t < NTV; ++t) {
;                 const LAS unsigned char* vb = vread + (32 * u) * RSV + 64 * t;
;                 const bf16x8 v0 = tr_pair(vb, vb + 4 * RSV), v1 = tr_pair(vb + 16 * RSV, vb + 20 * RSV);
;                 O[t] = __builtin_amdgcn_mfma_f32_32x32x16_bf16(v0, P0, O[t], 0, 0, 0);
;                 O[t] = __builtin_amdgcn_mfma_f32_32x32x16_bf16(v1, P1, O[t], 0, 0, 0);
;             }
.LBB0_103:
	v_sub_f32_e32 v1, v80, v202
	v_exp_f32_e32 v6, v1
	v_sub_f32_e32 v1, v81, v202
	v_exp_f32_e32 v8, v1
	v_sub_f32_e32 v1, v82, v202
	v_exp_f32_e32 v10, v1
	v_sub_f32_e32 v1, v83, v202
	v_exp_f32_e32 v12, v1
	v_sub_f32_e32 v1, v84, v202
	v_exp_f32_e32 v14, v1
	v_sub_f32_e32 v1, v85, v202
	v_exp_f32_e32 v80, v1
	v_sub_f32_e32 v1, v86, v202
	v_exp_f32_e32 v82, v1
	v_sub_f32_e32 v1, v87, v202
	v_exp_f32_e32 v84, v1
	v_sub_f32_e32 v1, v88, v202
	v_exp_f32_e32 v7, v1
	v_sub_f32_e32 v1, v89, v202
	v_exp_f32_e32 v9, v1
	v_sub_f32_e32 v1, v90, v202
	v_exp_f32_e32 v11, v1
	v_sub_f32_e32 v1, v91, v202
	v_exp_f32_e32 v13, v1
	v_sub_f32_e32 v1, v92, v202
	v_exp_f32_e32 v15, v1
	v_sub_f32_e32 v1, v93, v202
	v_exp_f32_e32 v81, v1
	v_sub_f32_e32 v1, v94, v202
	v_exp_f32_e32 v83, v1
	v_sub_f32_e32 v1, v95, v202
	v_exp_f32_e32 v85, v1
	v_pk_add_f32 v[2:3], v[6:7], v[8:9]
	v_pk_add_f32 v[4:5], v[10:11], v[12:13]
	v_pk_add_f32 v[86:87], v[82:83], v[84:85]
	v_pk_add_f32 v[2:3], v[2:3], v[4:5]
	v_pk_add_f32 v[4:5], v[14:15], v[80:81]
	s_nop 0
	v_pk_add_f32 v[4:5], v[4:5], v[86:87]
	s_nop 0
	v_pk_add_f32 v[2:3], v[2:3], v[4:5]
	v_cvt_pk_bf16_f32 v4, v14, v80
	v_add_f32_e32 v1, v2, v3
	v_cvt_pk_bf16_f32 v2, v6, v8
	v_cvt_pk_bf16_f32 v3, v10, v12
	v_cvt_pk_bf16_f32 v5, v82, v84
	v_cvt_pk_bf16_f32 v6, v7, v9
	v_cvt_pk_bf16_f32 v7, v11, v13
	v_cvt_pk_bf16_f32 v8, v15, v81
	v_cvt_pk_bf16_f32 v9, v83, v85
	ds_read_b64_tr_b16 v[80:81], v185 offset:36032
	ds_read_b64_tr_b16 v[82:83], v185 offset:37312
	s_waitcnt lgkmcnt(14)
	v_mfma_f32_32x32x16_bf16 v[64:79], v[212:215], v[2:5], v[64:79]
	v_add_f32_e32 v181, v181, v1
	s_waitcnt lgkmcnt(12)
	v_mfma_f32_32x32x16_bf16 v[64:79], v[216:219], v[6:9], v[64:79]
	s_waitcnt lgkmcnt(10)
	v_mfma_f32_32x32x16_bf16 v[48:63], v[222:225], v[2:5], v[48:63]
	s_waitcnt lgkmcnt(8)
	v_mfma_f32_32x32x16_bf16 v[48:63], v[226:229], v[6:9], v[48:63]
	s_waitcnt lgkmcnt(6)
	v_mfma_f32_32x32x16_bf16 v[32:47], v[230:233], v[2:5], v[32:47]
	s_waitcnt lgkmcnt(4)
	v_mfma_f32_32x32x16_bf16 v[32:47], v[238:241], v[6:9], v[32:47]
	s_waitcnt lgkmcnt(2)
	v_mfma_f32_32x32x16_bf16 v[16:31], v[242:245], v[2:5], v[16:31]
	s_waitcnt lgkmcnt(0)
	v_mfma_f32_32x32x16_bf16 v[16:31], v[80:83], v[6:9], v[16:31]

; #define LAS __attribute__((address_space(3)))
; __device__ __forceinline__ float xmax32(float v) { const auto r = __builtin_amdgcn_permlane32_swap(__float_as_uint(v), __float_as_uint(v), false, false); return __builtin_fmaxf(__uint_as_float(r[0]), __uint_as_float(r[1])); }
; template <int HD, int DV, int HW, int MODE> ...
;     ...
;             const int js = jc + 32 * u;
;             if (js + 31 < iw - HW || js > iw + 31 + HW || js + 31 < 0 || js >= L) continue;
;             f32x16 S;
; #pragma unroll
;             for (int i = 0; i < 16; ++i) S[i] = 0.f;
; #pragma unroll
;             for (int ks = 0; ks < KS; ++ks) { const bf16x8 kf = *(const LAS bf16x8*)(kread + (32 * u) * RSK + 32 * ks); S = __builtin_amdgcn_mfma_f32_32x32x16_bf16(kf, qf[ks], S, 0, 0, 0); }
;             const bool full = (js >= iw + 31 - HW) && (js + 31 <= iw + HW) && js >= 0 && js + 31 < L;
;             if (!full) {
;                 const int qi = iw + ql;
; #pragma unroll
;                 for (int i = 0; i < 16; ++i) { const int j = js + (i & 7) + 8 * hh + 16 * (i >> 3); const int d = qi - j; const bool ok = (d <= HW) && (d >= -HW) && (j >= 0) && (j < L); S[i] = ok ? S[i] : -INFINITY; }
;             }
;             float mt = xmax32(max16(S));
;             if (__any(mt > m + 8.0f)) {
;                 const float mn = fmaxf(m, mt), a = __builtin_amdgcn_exp2f(m - mn); l *= a; m = mn;
; #pragma unroll
;                 for (int t = 0; t < NTV; ++t) O[t] = O[t] * a;
;             }
; #pragma unroll
;             for (int i = 0; i < 16; ++i) S[i] = __builtin_amdgcn_exp2f(S[i] - m);
;             l += sum16(S);
;             const bf16x8 P0 = pack8(S, 0), P1 = pack8(S, 8);
; #pragma unroll
;             for (int t = 0; t < NTV; ++t) {
;                 const LAS unsigned char* vb = vread + (32 * u) * RSV + 64 * t;
;                 const bf16x8 v0 = tr_pair(vb, vb + 4 * RSV), v1 = tr_pair(vb + 16 * RSV, vb + 20 * RSV);
.LBB0_123:
	s_add_i32 s37, s34, s29
	s_sub_i32 s42, s37, 64
	s_sub_i32 s43, s37, 33
	s_cmp_lt_i32 s43, s4
	s_cselect_b64 s[10:11], -1, 0
	s_cmp_gt_i32 s42, s5
	s_cselect_b64 s[40:41], -1, 0
	s_cmpk_lt_i32 s42, 0xffe1
	s_cselect_b64 s[44:45], -1, 0
	s_or_b64 s[10:11], s[10:11], s[44:45]
	s_or_b64 s[10:11], s[10:11], s[40:41]
	s_cmp_ge_i32 s42, s27
	s_cselect_b64 s[40:41], -1, 0
	s_or_b64 s[10:11], s[40:41], s[10:11]
	s_and_b64 vcc, exec, s[10:11]
	s_cbranch_vccnz .LBB0_131
	ds_read_b128 v[2:5], v201
	ds_read_b128 v[212:215], v201 offset:32
	ds_read_b128 v[216:219], v201 offset:64
	ds_read_b128 v[222:225], v201 offset:96
	ds_read_b128 v[226:229], v201 offset:128
	ds_read_b128 v[230:233], v201 offset:160
	ds_read_b128 v[238:241], v201 offset:192
	ds_read_b128 v[242:245], v201 offset:224
	s_cmp_lt_i32 s42, s23
	s_cselect_b64 s[40:41], -1, 0
	s_and_b64 vcc, exec, s[40:41]
	s_waitcnt lgkmcnt(7)
	v_mfma_f32_32x32x16_bf16 v[80:95], v[2:5], v[96:99], 0
	s_waitcnt lgkmcnt(6)
	v_mfma_f32_32x32x16_bf16 v[80:95], v[212:215], v[100:103], v[80:95]
	s_waitcnt lgkmcnt(5)
	v_mfma_f32_32x32x16_bf16 v[80:95], v[216:219], v[104:107], v[80:95]
	s_waitcnt lgkmcnt(4)
	v_mfma_f32_32x32x16_bf16 v[80:95], v[222:225], v[108:111], v[80:95]
	s_waitcnt lgkmcnt(3)
	v_mfma_f32_32x32x16_bf16 v[80:95], v[226:229], v[112:115], v[80:95]
	s_waitcnt lgkmcnt(2)
	v_mfma_f32_32x32x16_bf16 v[80:95], v[230:233], v[116:119], v[80:95]
	s_waitcnt lgkmcnt(1)
	v_mfma_f32_32x32x16_bf16 v[80:95], v[238:241], v[120:123], v[80:95]
	s_waitcnt lgkmcnt(0)
	v_mfma_f32_32x32x16_bf16 v[80:95], v[242:245], v[124:127], v[80:95]
	ds_read_b64_tr_b16 v[212:213], v183 offset:34816
	ds_read_b64_tr_b16 v[214:215], v183 offset:36096
	ds_read_b64_tr_b16 v[216:217], v183 offset:39936
	ds_read_b64_tr_b16 v[218:219], v183 offset:41216
	ds_read_b64_tr_b16 v[222:223], v183 offset:34880
	ds_read_b64_tr_b16 v[224:225], v183 offset:36160
	ds_read_b64_tr_b16 v[226:227], v183 offset:40000
	ds_read_b64_tr_b16 v[228:229], v183 offset:41280
	ds_read_b64_tr_b16 v[230:231], v183 offset:34944
	ds_read_b64_tr_b16 v[232:233], v183 offset:36224
	ds_read_b64_tr_b16 v[238:239], v183 offset:40064
	ds_read_b64_tr_b16 v[240:241], v183 offset:41344
	ds_read_b64_tr_b16 v[242:243], v183 offset:35008
	ds_read_b64_tr_b16 v[244:245], v183 offset:36288
	s_cbranch_vccnz .LBB0_126
	s_cmp_gt_i32 s42, s28
	s_cselect_b64 s[10:11], -1, 0
	s_cmp_lt_i32 s42, 0
	s_cselect_b64 s[40:41], -1, 0
	s_or_b64 s[10:11], s[10:11], s[40:41]
	s_cmp_ge_i32 s43, s27
	s_cselect_b64 s[40:41], -1, 0
	s_or_b64 s[40:41], s[10:11], s[40:41]

; #define LAS __attribute__((address_space(3)))
; __device__ __forceinline__ float xmax32(float v) { const auto r = __builtin_amdgcn_permlane32_swap(__float_as_uint(v), __float_as_uint(v), false, false); return __builtin_fmaxf(__uint_as_float(r[0]), __uint_as_float(r[1])); }
; template <int HD, int DV, int HW, int MODE> ...
;     ...
;             const int js = jc + 32 * u;
;             if (js + 31 < iw - HW || js > iw + 31 + HW || js + 31 < 0 || js >= L) continue;
;             f32x16 S;
; #pragma unroll
;             for (int i = 0; i < 16; ++i) S[i] = 0.f;
; #pragma unroll
;             for (int ks = 0; ks < KS; ++ks) { const bf16x8 kf = *(const LAS bf16x8*)(kread + (32 * u) * RSK + 32 * ks); S = __builtin_amdgcn_mfma_f32_32x32x16_bf16(kf, qf[ks], S, 0, 0, 0); }
;             const bool full = (js >= iw + 31 - HW) && (js + 31 <= iw + HW) && js >= 0 && js + 31 < L;
;             if (!full) {
;                 const int qi = iw + ql;
; #pragma unroll
;                 for (int i = 0; i < 16; ++i) { const int j = js + (i & 7) + 8 * hh + 16 * (i >> 3); const int d = qi - j; const bool ok = (d <= HW) && (d >= -HW) && (j >= 0) && (j < L); S[i] = ok ? S[i] : -INFINITY; }
;             }
;             float mt = xmax32(max16(S));
;             if (__any(mt > m + 8.0f)) {
;                 const float mn = fmaxf(m, mt), a = __builtin_amdgcn_exp2f(m - mn); l *= a; m = mn;
; #pragma unroll
;                 for (int t = 0; t < NTV; ++t) O[t] = O[t] * a;
;             }
; #pragma unroll
;             for (int i = 0; i < 16; ++i) S[i] = __builtin_amdgcn_exp2f(S[i] - m);
;             l += sum16(S);
;             const bf16x8 P0 = pack8(S, 0), P1 = pack8(S, 8);
; #pragma unroll
;             for (int t = 0; t < NTV; ++t) {
;                 const LAS unsigned char* vb = vread + (32 * u) * RSV + 64 * t;
;                 const bf16x8 v0 = tr_pair(vb, vb + 4 * RSV), v1 = tr_pair(vb + 16 * RSV, vb + 20 * RSV);
;                 O[t] = __builtin_amdgcn_mfma_f32_32x32x16_bf16(v0, P0, O[t], 0, 0, 0);
;                 O[t] = __builtin_amdgcn_mfma_f32_32x32x16_bf16(v1, P1, O[t], 0, 0, 0);
;             }
.LBB0_130:
	v_sub_f32_e32 v1, v80, v202
	v_exp_f32_e32 v6, v1
	v_sub_f32_e32 v1, v81, v202
	v_exp_f32_e32 v8, v1
	v_sub_f32_e32 v1, v82, v202
	v_exp_f32_e32 v10, v1
	v_sub_f32_e32 v1, v83, v202
	v_exp_f32_e32 v12, v1
	v_sub_f32_e32 v1, v84, v202
	v_exp_f32_e32 v14, v1
	v_sub_f32_e32 v1, v85, v202
	v_exp_f32_e32 v80, v1
	v_sub_f32_e32 v1, v86, v202
	v_exp_f32_e32 v82, v1
	v_sub_f32_e32 v1, v87, v202
	v_exp_f32_e32 v84, v1
	v_sub_f32_e32 v1, v88, v202
	v_exp_f32_e32 v7, v1
	v_sub_f32_e32 v1, v89, v202
	v_exp_f32_e32 v9, v1
	v_sub_f32_e32 v1, v90, v202
	v_exp_f32_e32 v11, v1
	v_sub_f32_e32 v1, v91, v202
	v_exp_f32_e32 v13, v1
	v_sub_f32_e32 v1, v92, v202
	v_exp_f32_e32 v15, v1
	v_sub_f32_e32 v1, v93, v202
	v_exp_f32_e32 v81, v1
	v_sub_f32_e32 v1, v94, v202
	v_exp_f32_e32 v83, v1
	v_sub_f32_e32 v1, v95, v202
	v_exp_f32_e32 v85, v1
	v_pk_add_f32 v[2:3], v[6:7], v[8:9]
	v_pk_add_f32 v[4:5], v[10:11], v[12:13]
	v_pk_add_f32 v[86:87], v[82:83], v[84:85]
	v_pk_add_f32 v[2:3], v[2:3], v[4:5]
	v_pk_add_f32 v[4:5], v[14:15], v[80:81]
	s_nop 0
	v_pk_add_f32 v[4:5], v[4:5], v[86:87]
	s_nop 0
	v_pk_add_f32 v[2:3], v[2:3], v[4:5]
	v_cvt_pk_bf16_f32 v4, v14, v80
	v_add_f32_e32 v1, v2, v3
	v_cvt_pk_bf16_f32 v2, v6, v8
	v_cvt_pk_bf16_f32 v3, v10, v12
	v_cvt_pk_bf16_f32 v5, v82, v84
	v_cvt_pk_bf16_f32 v6, v7, v9
	v_cvt_pk_bf16_f32 v7, v11, v13
	v_cvt_pk_bf16_f32 v8, v15, v81
	v_cvt_pk_bf16_f32 v9, v83, v85
	ds_read_b64_tr_b16 v[80:81], v183 offset:40128
	ds_read_b64_tr_b16 v[82:83], v183 offset:41408
	s_waitcnt lgkmcnt(14)
	v_mfma_f32_32x32x16_bf16 v[64:79], v[212:215], v[2:5], v[64:79]
	v_add_f32_e32 v181, v181, v1
	s_waitcnt lgkmcnt(12)
	v_mfma_f32_32x32x16_bf16 v[64:79], v[216:219], v[6:9], v[64:79]
	s_waitcnt lgkmcnt(10)
	v_mfma_f32_32x32x16_bf16 v[48:63], v[222:225], v[2:5], v[48:63]
	s_waitcnt lgkmcnt(8)
	v_mfma_f32_32x32x16_bf16 v[48:63], v[226:229], v[6:9], v[48:63]
	s_waitcnt lgkmcnt(6)
	v_mfma_f32_32x32x16_bf16 v[32:47], v[230:233], v[2:5], v[32:47]
	s_waitcnt lgkmcnt(4)
	v_mfma_f32_32x32x16_bf16 v[32:47], v[238:241], v[6:9], v[32:47]
	s_waitcnt lgkmcnt(2)
	v_mfma_f32_32x32x16_bf16 v[16:31], v[242:245], v[2:5], v[16:31]
	s_waitcnt lgkmcnt(0)
	v_mfma_f32_32x32x16_bf16 v[16:31], v[80:83], v[6:9], v[16:31]
.LBB0_131:
	s_sub_i32 s44, s37, 32
	s_add_i32 s43, s37, -1
	s_cmp_lt_i32 s43, s4
	s_cselect_b64 s[10:11], -1, 0
	s_cmp_gt_i32 s44, s5
	s_cselect_b64 s[40:41], -1, 0
	s_cmpk_lt_i32 s42, 0xffc1
	s_cselect_b64 s[46:47], -1, 0
	s_or_b64 s[10:11], s[10:11], s[46:47]
	s_or_b64 s[10:11], s[10:11], s[40:41]
	s_cmp_ge_i32 s44, s27
	s_cselect_b64 s[40:41], -1, 0
	s_or_b64 s[10:11], s[40:41], s[10:11]
	s_and_b64 vcc, exec, s[10:11]
	s_cbranch_vccnz .LBB0_139
	ds_read_b128 v[2:5], v201 offset:8704
	ds_read_b128 v[212:215], v201 offset:8736
	ds_read_b128 v[216:219], v201 offset:8768
	ds_read_b128 v[222:225], v201 offset:8800
	ds_read_b128 v[226:229], v201 offset:8832
	ds_read_b128 v[230:233], v201 offset:8864
	ds_read_b128 v[238:241], v201 offset:8896
	ds_read_b128 v[242:245], v201 offset:8928
	s_cmp_lt_i32 s44, s23
	s_cselect_b64 s[40:41], -1, 0
	s_and_b64 vcc, exec, s[40:41]
	s_waitcnt lgkmcnt(7)
	v_mfma_f32_32x32x16_bf16 v[80:95], v[2:5], v[96:99], 0
	s_waitcnt lgkmcnt(6)
	v_mfma_f32_32x32x16_bf16 v[80:95], v[212:215], v[100:103], v[80:95]
	s_waitcnt lgkmcnt(5)
	v_mfma_f32_32x32x16_bf16 v[80:95], v[216:219], v[104:107], v[80:95]
	s_waitcnt lgkmcnt(4)
	v_mfma_f32_32x32x16_bf16 v[80:95], v[222:225], v[108:111], v[80:95]
	s_waitcnt lgkmcnt(3)
	v_mfma_f32_32x32x16_bf16 v[80:95], v[226:229], v[112:115], v[80:95]
	s_waitcnt lgkmcnt(2)
	v_mfma_f32_32x32x16_bf16 v[80:95], v[230:233], v[116:119], v[80:95]
	s_waitcnt lgkmcnt(1)
	v_mfma_f32_32x32x16_bf16 v[80:95], v[238:241], v[120:123], v[80:95]
	s_waitcnt lgkmcnt(0)
	v_mfma_f32_32x32x16_bf16 v[80:95], v[242:245], v[124:127], v[80:95]
	ds_read_b64_tr_b16 v[212:213], v183 offset:45056
	ds_read_b64_tr_b16 v[214:215], v183 offset:46336
	ds_read_b64_tr_b16 v[216:217], v183 offset:50176
	ds_read_b64_tr_b16 v[218:219], v183 offset:51456
	ds_read_b64_tr_b16 v[222:223], v183 offset:45120
	ds_read_b64_tr_b16 v[224:225], v183 offset:46400
	ds_read_b64_tr_b16 v[226:227], v183 offset:50240
	ds_read_b64_tr_b16 v[228:229], v183 offset:51520
	ds_read_b64_tr_b16 v[230:231], v183 offset:45184
	ds_read_b64_tr_b16 v[232:233], v183 offset:46464
	ds_read_b64_tr_b16 v[238:239], v183 offset:50304
	ds_read_b64_tr_b16 v[240:241], v183 offset:51584
	ds_read_b64_tr_b16 v[242:243], v183 offset:45248
	ds_read_b64_tr_b16 v[244:245], v183 offset:46528
	s_cbranch_vccnz .LBB0_134
	s_cmp_gt_i32 s44, s28
	s_cselect_b64 s[10:11], -1, 0
	s_cmpk_lt_i32 s42, 0xffe0
	s_cselect_b64 s[40:41], -1, 0
	s_or_b64 s[10:11], s[40:41], s[10:11]
	s_cmp_ge_i32 s43, s27
	s_cselect_b64 s[40:41], -1, 0
	s_or_b64 s[40:41], s[40:41], s[10:11]

; #define LAS __attribute__((address_space(3)))
; __device__ __forceinline__ float xmax32(float v) { const auto r = __builtin_amdgcn_permlane32_swap(__float_as_uint(v), __float_as_uint(v), false, false); return __builtin_fmaxf(__uint_as_float(r[0]), __uint_as_float(r[1])); }
; template <int HD, int DV, int HW, int MODE> ...
;     ...
;             const int js = jc + 32 * u;
;             if (js + 31 < iw - HW || js > iw + 31 + HW || js + 31 < 0 || js >= L) continue;
;             f32x16 S;
; #pragma unroll
;             for (int i = 0; i < 16; ++i) S[i] = 0.f;
; #pragma unroll
;             for (int ks = 0; ks < KS; ++ks) { const bf16x8 kf = *(const LAS bf16x8*)(kread + (32 * u) * RSK + 32 * ks); S = __builtin_amdgcn_mfma_f32_32x32x16_bf16(kf, qf[ks], S, 0, 0, 0); }
;             const bool full = (js >= iw + 31 - HW) && (js + 31 <= iw + HW) && js >= 0 && js + 31 < L;
;             if (!full) {
;                 const int qi = iw + ql;
; #pragma unroll
;                 for (int i = 0; i < 16; ++i) { const int j = js + (i & 7) + 8 * hh + 16 * (i >> 3); const int d = qi - j; const bool ok = (d <= HW) && (d >= -HW) && (j >= 0) && (j < L); S[i] = ok ? S[i] : -INFINITY; }
;             }
;             float mt = xmax32(max16(S));
;             if (__any(mt > m + 8.0f)) {
;                 const float mn = fmaxf(m, mt), a = __builtin_amdgcn_exp2f(m - mn); l *= a; m = mn;
; #pragma unroll
;                 for (int t = 0; t < NTV; ++t) O[t] = O[t] * a;
;             }
; #pragma unroll
;             for (int i = 0; i < 16; ++i) S[i] = __builtin_amdgcn_exp2f(S[i] - m);
;             l += sum16(S);
;             const bf16x8 P0 = pack8(S, 0), P1 = pack8(S, 8);
; #pragma unroll
;             for (int t = 0; t < NTV; ++t) {
;                 const LAS unsigned char* vb = vread + (32 * u) * RSV + 64 * t;
;                 const bf16x8 v0 = tr_pair(vb, vb + 4 * RSV), v1 = tr_pair(vb + 16 * RSV, vb + 20 * RSV);
;                 O[t] = __builtin_amdgcn_mfma_f32_32x32x16_bf16(v0, P0, O[t], 0, 0, 0);
;                 O[t] = __builtin_amdgcn_mfma_f32_32x32x16_bf16(v1, P1, O[t], 0, 0, 0);
;             }
.LBB0_138:
	v_sub_f32_e32 v1, v80, v202
	v_exp_f32_e32 v6, v1
	v_sub_f32_e32 v1, v81, v202
	v_exp_f32_e32 v8, v1
	v_sub_f32_e32 v1, v82, v202
	v_exp_f32_e32 v10, v1
	v_sub_f32_e32 v1, v83, v202
	v_exp_f32_e32 v12, v1
	v_sub_f32_e32 v1, v84, v202
	v_exp_f32_e32 v14, v1
	v_sub_f32_e32 v1, v85, v202
	v_exp_f32_e32 v80, v1
	v_sub_f32_e32 v1, v86, v202
	v_exp_f32_e32 v82, v1
	v_sub_f32_e32 v1, v87, v202
	v_exp_f32_e32 v84, v1
	v_sub_f32_e32 v1, v88, v202
	v_exp_f32_e32 v7, v1
	v_sub_f32_e32 v1, v89, v202
	v_exp_f32_e32 v9, v1
	v_sub_f32_e32 v1, v90, v202
	v_exp_f32_e32 v11, v1
	v_sub_f32_e32 v1, v91, v202
	v_exp_f32_e32 v13, v1
	v_sub_f32_e32 v1, v92, v202
	v_exp_f32_e32 v15, v1
	v_sub_f32_e32 v1, v93, v202
	v_exp_f32_e32 v81, v1
	v_sub_f32_e32 v1, v94, v202
	v_exp_f32_e32 v83, v1
	v_sub_f32_e32 v1, v95, v202
	v_exp_f32_e32 v85, v1
	v_pk_add_f32 v[2:3], v[6:7], v[8:9]
	v_pk_add_f32 v[4:5], v[10:11], v[12:13]
	v_pk_add_f32 v[86:87], v[82:83], v[84:85]
	v_pk_add_f32 v[2:3], v[2:3], v[4:5]
	v_pk_add_f32 v[4:5], v[14:15], v[80:81]
	s_nop 0
	v_pk_add_f32 v[4:5], v[4:5], v[86:87]
	s_nop 0
	v_pk_add_f32 v[2:3], v[2:3], v[4:5]
	v_cvt_pk_bf16_f32 v4, v14, v80
	v_add_f32_e32 v1, v2, v3
	v_cvt_pk_bf16_f32 v2, v6, v8
	v_cvt_pk_bf16_f32 v3, v10, v12
	v_cvt_pk_bf16_f32 v5, v82, v84
	v_cvt_pk_bf16_f32 v6, v7, v9
	v_cvt_pk_bf16_f32 v7, v11, v13
	v_cvt_pk_bf16_f32 v8, v15, v81
	v_cvt_pk_bf16_f32 v9, v83, v85
	ds_read_b64_tr_b16 v[80:81], v183 offset:50368
	ds_read_b64_tr_b16 v[82:83], v183 offset:51648
	s_waitcnt lgkmcnt(14)
	v_mfma_f32_32x32x16_bf16 v[64:79], v[212:215], v[2:5], v[64:79]
	v_add_f32_e32 v181, v181, v1
	s_waitcnt lgkmcnt(12)
	v_mfma_f32_32x32x16_bf16 v[64:79], v[216:219], v[6:9], v[64:79]
	s_waitcnt lgkmcnt(10)
	v_mfma_f32_32x32x16_bf16 v[48:63], v[222:225], v[2:5], v[48:63]
	s_waitcnt lgkmcnt(8)
	v_mfma_f32_32x32x16_bf16 v[48:63], v[226:229], v[6:9], v[48:63]
	s_waitcnt lgkmcnt(6)
	v_mfma_f32_32x32x16_bf16 v[32:47], v[230:233], v[2:5], v[32:47]
	s_waitcnt lgkmcnt(4)
	v_mfma_f32_32x32x16_bf16 v[32:47], v[238:241], v[6:9], v[32:47]
	s_waitcnt lgkmcnt(2)
	v_mfma_f32_32x32x16_bf16 v[16:31], v[242:245], v[2:5], v[16:31]
	s_waitcnt lgkmcnt(0)
	v_mfma_f32_32x32x16_bf16 v[16:31], v[80:83], v[6:9], v[16:31]
.LBB0_139:
	s_add_i32 s42, s37, 31
	s_cmp_lt_i32 s42, s4
	s_cselect_b64 s[10:11], -1, 0
	s_cmp_gt_i32 s37, s5
	s_cselect_b64 s[40:41], -1, 0
	s_or_b64 s[10:11], s[10:11], s[40:41]
	s_cmp_ge_u32 s37, s27
	s_cselect_b64 s[40:41], -1, 0
	s_or_b64 s[10:11], s[40:41], s[10:11]
	s_and_b64 vcc, exec, s[10:11]
	s_cbranch_vccnz .LBB0_147
	ds_read_b128 v[2:5], v201 offset:17408
	ds_read_b128 v[212:215], v201 offset:17440
	ds_read_b128 v[216:219], v201 offset:17472
	ds_read_b128 v[222:225], v201 offset:17504
	ds_read_b128 v[226:229], v201 offset:17536
	ds_read_b128 v[230:233], v201 offset:17568
	ds_read_b128 v[238:241], v201 offset:17600
	ds_read_b128 v[242:245], v201 offset:17632
	s_cmp_lt_i32 s37, s23
	s_cselect_b64 s[40:41], -1, 0
	s_and_b64 vcc, exec, s[40:41]
	s_waitcnt lgkmcnt(7)
	v_mfma_f32_32x32x16_bf16 v[80:95], v[2:5], v[96:99], 0
	s_waitcnt lgkmcnt(6)
	v_mfma_f32_32x32x16_bf16 v[80:95], v[212:215], v[100:103], v[80:95]
	s_waitcnt lgkmcnt(5)
	v_mfma_f32_32x32x16_bf16 v[80:95], v[216:219], v[104:107], v[80:95]
	s_waitcnt lgkmcnt(4)
	v_mfma_f32_32x32x16_bf16 v[80:95], v[222:225], v[108:111], v[80:95]
	s_waitcnt lgkmcnt(3)
	v_mfma_f32_32x32x16_bf16 v[80:95], v[226:229], v[112:115], v[80:95]
	s_waitcnt lgkmcnt(2)
	v_mfma_f32_32x32x16_bf16 v[80:95], v[230:233], v[116:119], v[80:95]
	s_waitcnt lgkmcnt(1)
	v_mfma_f32_32x32x16_bf16 v[80:95], v[238:241], v[120:123], v[80:95]
	s_waitcnt lgkmcnt(0)
	v_mfma_f32_32x32x16_bf16 v[80:95], v[242:245], v[124:127], v[80:95]
	ds_read_b64_tr_b16 v[212:213], v183 offset:55296
	ds_read_b64_tr_b16 v[214:215], v183 offset:56576
	ds_read_b64_tr_b16 v[216:217], v183 offset:60416
	ds_read_b64_tr_b16 v[218:219], v183 offset:61696
	ds_read_b64_tr_b16 v[222:223], v183 offset:55360
	ds_read_b64_tr_b16 v[224:225], v183 offset:56640
	ds_read_b64_tr_b16 v[226:227], v183 offset:60480
	ds_read_b64_tr_b16 v[228:229], v183 offset:61760
	ds_read_b64_tr_b16 v[230:231], v183 offset:55424
	ds_read_b64_tr_b16 v[232:233], v183 offset:56704
	ds_read_b64_tr_b16 v[238:239], v183 offset:60544
	ds_read_b64_tr_b16 v[240:241], v183 offset:61824
	ds_read_b64_tr_b16 v[242:243], v183 offset:55488
	ds_read_b64_tr_b16 v[244:245], v183 offset:56768
	s_cbranch_vccnz .LBB0_142
	s_cmp_gt_i32 s37, s28
	s_cselect_b64 s[10:11], -1, 0
	s_cmp_ge_u32 s42, s27
	s_cselect_b64 s[40:41], -1, 0
	s_or_b64 s[40:41], s[10:11], s[40:41]

; #define LAS __attribute__((address_space(3)))
; __device__ __forceinline__ float xmax32(float v) { const auto r = __builtin_amdgcn_permlane32_swap(__float_as_uint(v), __float_as_uint(v), false, false); return __builtin_fmaxf(__uint_as_float(r[0]), __uint_as_float(r[1])); }
; template <int HD, int DV, int HW, int MODE> ...
;     ...
;             const int js = jc + 32 * u;
;             if (js + 31 < iw - HW || js > iw + 31 + HW || js + 31 < 0 || js >= L) continue;
;             f32x16 S;
; #pragma unroll
;             for (int i = 0; i < 16; ++i) S[i] = 0.f;
; #pragma unroll
;             for (int ks = 0; ks < KS; ++ks) { const bf16x8 kf = *(const LAS bf16x8*)(kread + (32 * u) * RSK + 32 * ks); S = __builtin_amdgcn_mfma_f32_32x32x16_bf16(kf, qf[ks], S, 0, 0, 0); }
;             const bool full = (js >= iw + 31 - HW) && (js + 31 <= iw + HW) && js >= 0 && js + 31 < L;
;             if (!full) {
;                 const int qi = iw + ql;
; #pragma unroll
;                 for (int i = 0; i < 16; ++i) { const int j = js + (i & 7) + 8 * hh + 16 * (i >> 3); const int d = qi - j; const bool ok = (d <= HW) && (d >= -HW) && (j >= 0) && (j < L); S[i] = ok ? S[i] : -INFINITY; }
;             }
;             float mt = xmax32(max16(S));
;             if (__any(mt > m + 8.0f)) {
;                 const float mn = fmaxf(m, mt), a = __builtin_amdgcn_exp2f(m - mn); l *= a; m = mn;
; #pragma unroll
;                 for (int t = 0; t < NTV; ++t) O[t] = O[t] * a;
;             }
; #pragma unroll
;             for (int i = 0; i < 16; ++i) S[i] = __builtin_amdgcn_exp2f(S[i] - m);
;             l += sum16(S);
;             const bf16x8 P0 = pack8(S, 0), P1 = pack8(S, 8);
; #pragma unroll
;             for (int t = 0; t < NTV; ++t) {
;                 const LAS unsigned char* vb = vread + (32 * u) * RSV + 64 * t;
;                 const bf16x8 v0 = tr_pair(vb, vb + 4 * RSV), v1 = tr_pair(vb + 16 * RSV, vb + 20 * RSV);
;                 O[t] = __builtin_amdgcn_mfma_f32_32x32x16_bf16(v0, P0, O[t], 0, 0, 0);
;                 O[t] = __builtin_amdgcn_mfma_f32_32x32x16_bf16(v1, P1, O[t], 0, 0, 0);
;             }
.LBB0_146:
	v_sub_f32_e32 v1, v80, v202
	v_exp_f32_e32 v6, v1
	v_sub_f32_e32 v1, v81, v202
	v_exp_f32_e32 v8, v1
	v_sub_f32_e32 v1, v82, v202
	v_exp_f32_e32 v10, v1
	v_sub_f32_e32 v1, v83, v202
	v_exp_f32_e32 v12, v1
	v_sub_f32_e32 v1, v84, v202
	v_exp_f32_e32 v14, v1
	v_sub_f32_e32 v1, v85, v202
	v_exp_f32_e32 v80, v1
	v_sub_f32_e32 v1, v86, v202
	v_exp_f32_e32 v82, v1
	v_sub_f32_e32 v1, v87, v202
	v_exp_f32_e32 v84, v1
	v_sub_f32_e32 v1, v88, v202
	v_exp_f32_e32 v7, v1
	v_sub_f32_e32 v1, v89, v202
	v_exp_f32_e32 v9, v1
	v_sub_f32_e32 v1, v90, v202
	v_exp_f32_e32 v11, v1
	v_sub_f32_e32 v1, v91, v202
	v_exp_f32_e32 v13, v1
	v_sub_f32_e32 v1, v92, v202
	v_exp_f32_e32 v15, v1
	v_sub_f32_e32 v1, v93, v202
	v_exp_f32_e32 v81, v1
	v_sub_f32_e32 v1, v94, v202
	v_exp_f32_e32 v83, v1
	v_sub_f32_e32 v1, v95, v202
	v_exp_f32_e32 v85, v1
	v_pk_add_f32 v[2:3], v[6:7], v[8:9]
	v_pk_add_f32 v[4:5], v[10:11], v[12:13]
	v_pk_add_f32 v[86:87], v[82:83], v[84:85]
	v_pk_add_f32 v[2:3], v[2:3], v[4:5]
	v_pk_add_f32 v[4:5], v[14:15], v[80:81]
	s_nop 0
	v_pk_add_f32 v[4:5], v[4:5], v[86:87]
	s_nop 0
	v_pk_add_f32 v[2:3], v[2:3], v[4:5]
	v_cvt_pk_bf16_f32 v4, v14, v80
	v_add_f32_e32 v1, v2, v3
	v_cvt_pk_bf16_f32 v2, v6, v8
	v_cvt_pk_bf16_f32 v3, v10, v12
	v_cvt_pk_bf16_f32 v5, v82, v84
	v_cvt_pk_bf16_f32 v6, v7, v9
	v_cvt_pk_bf16_f32 v7, v11, v13
	v_cvt_pk_bf16_f32 v8, v15, v81
	v_cvt_pk_bf16_f32 v9, v83, v85
	ds_read_b64_tr_b16 v[80:81], v183 offset:60608
	ds_read_b64_tr_b16 v[82:83], v183 offset:61888
	s_waitcnt lgkmcnt(14)
	v_mfma_f32_32x32x16_bf16 v[64:79], v[212:215], v[2:5], v[64:79]
	v_add_f32_e32 v181, v181, v1
	s_waitcnt lgkmcnt(12)
	v_mfma_f32_32x32x16_bf16 v[64:79], v[216:219], v[6:9], v[64:79]
	s_waitcnt lgkmcnt(10)
	v_mfma_f32_32x32x16_bf16 v[48:63], v[222:225], v[2:5], v[48:63]
	s_waitcnt lgkmcnt(8)
	v_mfma_f32_32x32x16_bf16 v[48:63], v[226:229], v[6:9], v[48:63]
	s_waitcnt lgkmcnt(6)
	v_mfma_f32_32x32x16_bf16 v[32:47], v[230:233], v[2:5], v[32:47]
	s_waitcnt lgkmcnt(4)
	v_mfma_f32_32x32x16_bf16 v[32:47], v[238:241], v[6:9], v[32:47]
	s_waitcnt lgkmcnt(2)
	v_mfma_f32_32x32x16_bf16 v[16:31], v[242:245], v[2:5], v[16:31]
	s_waitcnt lgkmcnt(0)
	v_mfma_f32_32x32x16_bf16 v[16:31], v[80:83], v[6:9], v[16:31]
.LBB0_147:
	s_add_i32 s42, s37, 32
	s_add_i32 s37, s37, 63
	s_cmp_lt_i32 s37, s4
	s_cselect_b64 s[10:11], -1, 0
	s_cmp_gt_i32 s42, s5
	s_cselect_b64 s[40:41], -1, 0
	s_or_b64 s[10:11], s[10:11], s[40:41]
	s_cmp_ge_u32 s42, s27
	s_cselect_b64 s[40:41], -1, 0
	s_or_b64 s[10:11], s[40:41], s[10:11]
	s_and_b64 vcc, exec, s[10:11]
	s_cbranch_vccnz .LBB0_104
	ds_read_b128 v[2:5], v201 offset:26112
	ds_read_b128 v[212:215], v201 offset:26144
	ds_read_b128 v[216:219], v201 offset:26176
	ds_read_b128 v[222:225], v201 offset:26208
	ds_read_b128 v[226:229], v201 offset:26240
	ds_read_b128 v[230:233], v201 offset:26272
	ds_read_b128 v[238:241], v201 offset:26304
	ds_read_b128 v[242:245], v201 offset:26336
	s_cmp_lt_i32 s42, s23
	s_cselect_b64 s[40:41], -1, 0
	s_and_b64 vcc, exec, s[40:41]
	s_waitcnt lgkmcnt(7)
	v_mfma_f32_32x32x16_bf16 v[80:95], v[2:5], v[96:99], 0
	s_waitcnt lgkmcnt(6)
	v_mfma_f32_32x32x16_bf16 v[80:95], v[212:215], v[100:103], v[80:95]
	s_waitcnt lgkmcnt(5)
	v_mfma_f32_32x32x16_bf16 v[80:95], v[216:219], v[104:107], v[80:95]
	s_waitcnt lgkmcnt(4)
	v_mfma_f32_32x32x16_bf16 v[80:95], v[222:225], v[108:111], v[80:95]
	s_waitcnt lgkmcnt(3)
	v_mfma_f32_32x32x16_bf16 v[80:95], v[226:229], v[112:115], v[80:95]
	s_waitcnt lgkmcnt(2)
	v_mfma_f32_32x32x16_bf16 v[80:95], v[230:233], v[116:119], v[80:95]
	s_waitcnt lgkmcnt(1)
	v_mfma_f32_32x32x16_bf16 v[80:95], v[238:241], v[120:123], v[80:95]
	s_waitcnt lgkmcnt(0)
	v_mfma_f32_32x32x16_bf16 v[80:95], v[242:245], v[124:127], v[80:95]
	ds_read_b64_tr_b16 v[212:213], v185 offset:30720
	ds_read_b64_tr_b16 v[214:215], v185 offset:32000
	ds_read_b64_tr_b16 v[216:217], v185 offset:35840
	ds_read_b64_tr_b16 v[218:219], v185 offset:37120
	ds_read_b64_tr_b16 v[222:223], v185 offset:30784
	ds_read_b64_tr_b16 v[224:225], v185 offset:32064
	ds_read_b64_tr_b16 v[226:227], v185 offset:35904
	ds_read_b64_tr_b16 v[228:229], v185 offset:37184
	ds_read_b64_tr_b16 v[230:231], v185 offset:30848
	ds_read_b64_tr_b16 v[232:233], v185 offset:32128
	ds_read_b64_tr_b16 v[238:239], v185 offset:35968
	ds_read_b64_tr_b16 v[240:241], v185 offset:37248
	ds_read_b64_tr_b16 v[242:243], v185 offset:30912
	ds_read_b64_tr_b16 v[244:245], v185 offset:32192
	s_cbranch_vccnz .LBB0_150
	s_cmp_gt_i32 s42, s28
	s_cselect_b64 s[10:11], -1, 0
	s_cmp_ge_u32 s37, s27
	s_cselect_b64 s[40:41], -1, 0
	s_or_b64 s[40:41], s[10:11], s[40:41]

; #define GM_WAIT_V(n) asm volatile("s_waitcnt vmcnt(" #n ")" ::: "memory")
; #define GM_WAIT_L(n) asm volatile("s_waitcnt lgkmcnt(" #n ")" ::: "memory")
; #define GM_BAR __builtin_amdgcn_s_barrier()
; #define GM_SCHED __builtin_amdgcn_sched_barrier(0)
; #define GM_LDA(dst, b, h) _Pragma("unroll") for (int m = 0; m < 4; ++m) _Pragma("unroll") for (int k = 0; k < 2; ++k) \
;         dst[m][k] = *(const LAS bf16x8*)(GM_SA(b, h) + aoff + (m * 2 + k) * 1024)
; #define GM_LDB(dst, b, h) _Pragma("unroll") for (int n = 0; n < 2; ++n) _Pragma("unroll") for (int k = 0; k < 2; ++k) \
;         dst[n][k] = *(const LAS bf16x8*)(GM_SB(b, h) + boff + (n * 2 + k) * 1024)
; #define GM_MMA(ai, bj, At, Bv) do { __builtin_amdgcn_s_setprio(1); \
;         _Pragma("unroll") for (int m = 0; m < 4; ++m) _Pragma("unroll") for (int n = 0; n < 2; ++n) _Pragma("unroll") for (int k = 0; k < 2; ++k) \
;             acc[ai][bj][m][n] = __builtin_amdgcn_mfma_f32_16x16x32_bf16(Bv[n][k], At[m][k], acc[ai][bj][m][n], 0, 0, 0); \
;         __builtin_amdgcn_s_setprio(0); } while (0)
; template <class Epi>
; __device__ __forceinline__ void gemm_phase(const bf16_t* __restrict__ A, const bf16_t* __restrict__ Bt, int M, int N, LAS unsigned char* lds, const Epi& epi, int vcu) {
;     ...
;             GM_LDB(B0, 0, 0); GM_SCHED; GM_LDA(At, 0, 0); GM_STAGE(GM_SA(1, 1), A, brow + HALF, t + 1);
;             GM_WAIT_L(8); GM_BAR; GM_WAIT_L(0); GM_MMA(0, 0, At, B0); GM_BAR; GM_SCHED;
;             GM_LDB(B1, 0, 1); GM_STAGE(GM_SB(0, 0), Bt, pcol, k2);
;             GM_BAR; GM_WAIT_L(0); GM_MMA(0, 1, At, B1); GM_BAR;
;             GM_LDA(At, 0, 1); GM_STAGE(GM_SA(0, 0), A, prow, k2);
;             GM_BAR; GM_WAIT_L(0); GM_MMA(1, 0, At, B0); GM_BAR; GM_SCHED;
;             GM_STAGE(GM_SB(0, 1), Bt, pcol + HALF, k2);
;             GM_WAIT_V(6); GM_BAR; GM_MMA(1, 1, At, B1); GM_BAR;
.LBB0_339:
	s_add_i32 s37, s37, 2
	v_add_u32_e32 v149, s88, v147
	s_cmp_gt_u32 s37, 13
	ds_read_b128 v[150:153], v149
	ds_read_b128 v[154:157], v149 offset:1024
	ds_read_b128 v[158:161], v149 offset:2048
	ds_read_b128 v[162:165], v149 offset:3072
	s_cselect_b64 s[48:49], -1, 0
	s_and_b64 s[48:49], s[48:49], exec
	s_cselect_b32 s48, 64, s43
	s_sub_i32 s10, s43, 64
	s_cmp_gt_u32 s37, 13
	s_cselect_b64 s[52:53], -1, 0
	s_and_b64 vcc, s[52:53], exec
	s_cselect_b32 s54, s29, s42
	s_cselect_b32 s52, s28, s44
	s_cselect_b32 s96, 0, s10
	v_add_u32_e32 v199, 0xc000, v133
	v_mov_b32_e32 v149, v130
	v_mov_b32_e32 v198, v1
	v_readfirstlane_b32 s10, v199
	ds_read_b128 v[166:169], v148
	ds_read_b128 v[170:173], v148 offset:1024
	ds_read_b128 v[174:177], v148 offset:2048
	ds_read_b128 v[178:181], v148 offset:3072
	ds_read_b128 v[182:185], v148 offset:4096
	ds_read_b128 v[186:189], v148 offset:5120
	ds_read_b128 v[190:193], v148 offset:6144
	ds_read_b128 v[194:197], v148 offset:7168
	s_mov_b32 m0, s10
	s_nop 0
	global_load_lds_dwordx4 v198, s[46:47]
	v_add_u32_e32 v198, 0xe000, v133
	s_nop 0
	v_readfirstlane_b32 s10, v198
	s_mov_b32 m0, s10
	s_nop 0
	global_load_lds_dwordx4 v149, s[46:47]
	s_waitcnt lgkmcnt(8)
	s_barrier
	s_waitcnt lgkmcnt(0)
	s_setprio 1
	s_waitcnt lgkmcnt(0)
	v_mfma_f32_16x16x32_bf16 v[126:129], v[150:153], v[166:169], v[126:129]
	v_mfma_f32_16x16x32_bf16 v[122:125], v[158:161], v[166:169], v[122:125]
	v_mfma_f32_16x16x32_bf16 v[110:113], v[150:153], v[174:177], v[110:113]
	v_mfma_f32_16x16x32_bf16 v[106:109], v[158:161], v[174:177], v[106:109]
	v_mfma_f32_16x16x32_bf16 v[94:97], v[150:153], v[182:185], v[94:97]
	v_mfma_f32_16x16x32_bf16 v[90:93], v[158:161], v[182:185], v[90:93]
	v_mfma_f32_16x16x32_bf16 v[78:81], v[150:153], v[190:193], v[78:81]
	v_mfma_f32_16x16x32_bf16 v[74:77], v[158:161], v[190:193], v[74:77]
	v_mfma_f32_16x16x32_bf16 v[126:129], v[154:157], v[170:173], v[126:129]
	v_mfma_f32_16x16x32_bf16 v[122:125], v[162:165], v[170:173], v[122:125]
	v_mfma_f32_16x16x32_bf16 v[110:113], v[154:157], v[178:181], v[110:113]
	v_mfma_f32_16x16x32_bf16 v[106:109], v[162:165], v[178:181], v[106:109]
	v_mfma_f32_16x16x32_bf16 v[94:97], v[154:157], v[186:189], v[94:97]
	v_mfma_f32_16x16x32_bf16 v[90:93], v[162:165], v[186:189], v[90:93]
	v_mfma_f32_16x16x32_bf16 v[78:81], v[154:157], v[194:197], v[78:81]
	v_mfma_f32_16x16x32_bf16 v[74:77], v[162:165], v[194:197], v[74:77]
	s_setprio 0
	s_barrier
	s_ashr_i32 s53, s52, 31
	s_lshl_b64 s[56:57], s[52:53], 11
	s_add_u32 s10, s25, s56
	s_addc_u32 s11, s34, s57
	s_lshl_b64 s[56:57], s[96:97], 1
	v_add_u32_e32 v149, s89, v147
	s_add_u32 s64, s10, s56
	v_readfirstlane_b32 s45, v131
	ds_read_b128 v[198:201], v149
	ds_read_b128 v[202:205], v149 offset:1024
	ds_read_b128 v[212:215], v149 offset:2048
	ds_read_b128 v[216:219], v149 offset:3072
	s_addc_u32 s65, s11, s57
	v_mov_b32_e32 v149, v130
	v_mov_b32_e32 v208, v1
	s_mov_b32 m0, s45
	v_readfirstlane_b32 s45, v132
	s_nop 0
	global_load_lds_dwordx4 v208, s[64:65]
	s_mov_b32 m0, s45
	s_nop 0
	global_load_lds_dwordx4 v149, s[64:65]
	s_barrier
	s_waitcnt lgkmcnt(0)
	s_setprio 1
	s_waitcnt lgkmcnt(0)
	v_mfma_f32_16x16x32_bf16 v[118:121], v[198:201], v[166:169], v[118:121]
	v_mfma_f32_16x16x32_bf16 v[114:117], v[212:215], v[166:169], v[114:117]
	v_mfma_f32_16x16x32_bf16 v[102:105], v[198:201], v[174:177], v[102:105]
	v_mfma_f32_16x16x32_bf16 v[98:101], v[212:215], v[174:177], v[98:101]
	v_mfma_f32_16x16x32_bf16 v[86:89], v[198:201], v[182:185], v[86:89]
	v_mfma_f32_16x16x32_bf16 v[82:85], v[212:215], v[182:185], v[82:85]
	v_mfma_f32_16x16x32_bf16 v[70:73], v[198:201], v[190:193], v[70:73]
	v_mfma_f32_16x16x32_bf16 v[66:69], v[212:215], v[190:193], v[66:69]
	v_mfma_f32_16x16x32_bf16 v[118:121], v[202:205], v[170:173], v[118:121]
	v_mfma_f32_16x16x32_bf16 v[114:117], v[216:219], v[170:173], v[114:117]
	v_mfma_f32_16x16x32_bf16 v[102:105], v[202:205], v[178:181], v[102:105]
	v_mfma_f32_16x16x32_bf16 v[98:101], v[216:219], v[178:181], v[98:101]
	v_mfma_f32_16x16x32_bf16 v[86:89], v[202:205], v[186:189], v[86:89]
	v_mfma_f32_16x16x32_bf16 v[82:85], v[216:219], v[186:189], v[82:85]
	v_mfma_f32_16x16x32_bf16 v[70:73], v[202:205], v[194:197], v[70:73]
	v_mfma_f32_16x16x32_bf16 v[66:69], v[216:219], v[194:197], v[66:69]
	s_setprio 0
	s_ashr_i32 s55, s54, 31
	s_lshl_b64 s[54:55], s[54:55], 11
	s_add_u32 s45, s74, s54
	s_addc_u32 s51, s75, s55
	s_add_u32 s54, s45, s56
	v_readfirstlane_b32 s49, v133
	s_addc_u32 s55, s51, s57
	v_mov_b32_e32 v149, v130
	v_mov_b32_e32 v208, v1
	s_mov_b32 m0, s49
	v_readfirstlane_b32 s49, v134
	s_barrier
	ds_read_b128 v[166:169], v148 offset:16384
	ds_read_b128 v[170:173], v148 offset:17408
	ds_read_b128 v[174:177], v148 offset:18432
	ds_read_b128 v[178:181], v148 offset:19456
	ds_read_b128 v[182:185], v148 offset:20480
	ds_read_b128 v[186:189], v148 offset:21504
	ds_read_b128 v[190:193], v148 offset:22528
	ds_read_b128 v[194:197], v148 offset:23552
	s_nop 0
	global_load_lds_dwordx4 v208, s[54:55]
	s_mov_b32 m0, s49
	s_nop 0
	global_load_lds_dwordx4 v149, s[54:55]
	s_barrier
; #define GM_WAIT_V(n) asm volatile("s_waitcnt vmcnt(" #n ")" ::: "memory")
; #define GM_WAIT_L(n) asm volatile("s_waitcnt lgkmcnt(" #n ")" ::: "memory")
; #define GM_BAR __builtin_amdgcn_s_barrier()
; #define GM_SCHED __builtin_amdgcn_sched_barrier(0)
; #define GM_LDA(dst, b, h) _Pragma("unroll") for (int m = 0; m < 4; ++m) _Pragma("unroll") for (int k = 0; k < 2; ++k) \
;         dst[m][k] = *(const LAS bf16x8*)(GM_SA(b, h) + aoff + (m * 2 + k) * 1024)
; #define GM_LDB(dst, b, h) _Pragma("unroll") for (int n = 0; n < 2; ++n) _Pragma("unroll") for (int k = 0; k < 2; ++k) \
;         dst[n][k] = *(const LAS bf16x8*)(GM_SB(b, h) + boff + (n * 2 + k) * 1024)
; #define GM_MMA(ai, bj, At, Bv) do { __builtin_amdgcn_s_setprio(1); \
;         _Pragma("unroll") for (int m = 0; m < 4; ++m) _Pragma("unroll") for (int n = 0; n < 2; ++n) _Pragma("unroll") for (int k = 0; k < 2; ++k) \
;             acc[ai][bj][m][n] = __builtin_amdgcn_mfma_f32_16x16x32_bf16(Bv[n][k], At[m][k], acc[ai][bj][m][n], 0, 0, 0); \
;         __builtin_amdgcn_s_setprio(0); } while (0)
; template <class Epi>
; __device__ __forceinline__ void gemm_phase(const bf16_t* __restrict__ A, const bf16_t* __restrict__ Bt, int M, int N, LAS unsigned char* lds, const Epi& epi, int vcu) {
;     ...
;             GM_BAR; GM_WAIT_L(0); GM_MMA(1, 0, At, B0); GM_BAR; GM_SCHED;
;             GM_STAGE(GM_SB(0, 1), Bt, pcol + HALF, k2);
;             GM_WAIT_V(6); GM_BAR; GM_MMA(1, 1, At, B1); GM_BAR;
;             GM_LDB(B0, 1, 0); GM_SCHED; GM_LDA(At, 1, 0); GM_STAGE(GM_SA(0, 1), A, prow + HALF, k2);
;             GM_WAIT_L(8); GM_BAR; GM_WAIT_L(0); GM_MMA(0, 0, At, B0); GM_BAR; GM_SCHED;
;             GM_LDB(B1, 1, 1); GM_STAGE(GM_SB(1, 0), Bt, pcol, k3);
;             GM_BAR; GM_WAIT_L(0); GM_MMA(0, 1, At, B1); GM_BAR;
	s_waitcnt lgkmcnt(0)
	s_setprio 1
	s_waitcnt lgkmcnt(0)
	v_mfma_f32_16x16x32_bf16 v[62:65], v[150:153], v[166:169], v[62:65]
	v_mfma_f32_16x16x32_bf16 v[58:61], v[158:161], v[166:169], v[58:61]
	v_mfma_f32_16x16x32_bf16 v[46:49], v[150:153], v[174:177], v[46:49]
	v_mfma_f32_16x16x32_bf16 v[42:45], v[158:161], v[174:177], v[42:45]
	v_mfma_f32_16x16x32_bf16 v[30:33], v[150:153], v[182:185], v[30:33]
	v_mfma_f32_16x16x32_bf16 v[26:29], v[158:161], v[182:185], v[26:29]
	v_mfma_f32_16x16x32_bf16 v[14:17], v[150:153], v[190:193], v[14:17]
	v_mfma_f32_16x16x32_bf16 v[10:13], v[158:161], v[190:193], v[10:13]
	v_mfma_f32_16x16x32_bf16 v[62:65], v[154:157], v[170:173], v[62:65]
	v_mfma_f32_16x16x32_bf16 v[58:61], v[162:165], v[170:173], v[58:61]
	v_mfma_f32_16x16x32_bf16 v[46:49], v[154:157], v[178:181], v[46:49]
	v_mfma_f32_16x16x32_bf16 v[42:45], v[162:165], v[178:181], v[42:45]
	v_mfma_f32_16x16x32_bf16 v[30:33], v[154:157], v[186:189], v[30:33]
	v_mfma_f32_16x16x32_bf16 v[26:29], v[162:165], v[186:189], v[26:29]
	v_mfma_f32_16x16x32_bf16 v[14:17], v[154:157], v[194:197], v[14:17]
	v_mfma_f32_16x16x32_bf16 v[10:13], v[162:165], v[194:197], v[10:13]
	s_setprio 0
	s_barrier
	s_bitset1_b32 s52, 7
	s_ashr_i32 s53, s52, 31
	s_lshl_b64 s[52:53], s[52:53], 11
	s_add_u32 s58, s25, s52
	s_addc_u32 s59, s34, s53
	s_add_u32 s52, s58, s56
	v_readfirstlane_b32 s49, v135
	s_addc_u32 s53, s59, s57
	v_mov_b32_e32 v149, v130
	v_mov_b32_e32 v150, v1
	s_mov_b32 m0, s49
	v_readfirstlane_b32 s49, v136
	s_nop 0
	global_load_lds_dwordx4 v150, s[52:53]
	s_mov_b32 m0, s49
	s_nop 0
	global_load_lds_dwordx4 v149, s[52:53]
	s_waitcnt vmcnt(6)
	s_barrier
	s_setprio 1
	v_mfma_f32_16x16x32_bf16 v[54:57], v[198:201], v[166:169], v[54:57]
	v_mfma_f32_16x16x32_bf16 v[50:53], v[212:215], v[166:169], v[50:53]
	v_mfma_f32_16x16x32_bf16 v[38:41], v[198:201], v[174:177], v[38:41]
	v_mfma_f32_16x16x32_bf16 v[34:37], v[212:215], v[174:177], v[34:37]
	v_mfma_f32_16x16x32_bf16 v[22:25], v[198:201], v[182:185], v[22:25]
	v_mfma_f32_16x16x32_bf16 v[18:21], v[212:215], v[182:185], v[18:21]
	v_mfma_f32_16x16x32_bf16 v[6:9], v[198:201], v[190:193], v[6:9]
	v_mfma_f32_16x16x32_bf16 v[2:5], v[212:215], v[190:193], v[2:5]
	v_mfma_f32_16x16x32_bf16 v[54:57], v[202:205], v[170:173], v[54:57]
	v_mfma_f32_16x16x32_bf16 v[50:53], v[216:219], v[170:173], v[50:53]
	v_mfma_f32_16x16x32_bf16 v[38:41], v[202:205], v[178:181], v[38:41]
	v_mfma_f32_16x16x32_bf16 v[34:37], v[216:219], v[178:181], v[34:37]
	v_mfma_f32_16x16x32_bf16 v[22:25], v[202:205], v[186:189], v[22:25]
	v_mfma_f32_16x16x32_bf16 v[18:21], v[216:219], v[186:189], v[18:21]
	v_mfma_f32_16x16x32_bf16 v[6:9], v[202:205], v[194:197], v[6:9]
	v_mfma_f32_16x16x32_bf16 v[2:5], v[216:219], v[194:197], v[2:5]
	s_setprio 0
	v_add_u32_e32 v149, s16, v147
	s_barrier
	ds_read_b128 v[150:153], v149
	ds_read_b128 v[154:157], v149 offset:1024
	ds_read_b128 v[158:161], v149 offset:2048
	ds_read_b128 v[162:165], v149 offset:3072
	s_add_u32 s52, s54, 0x40000
	v_readfirstlane_b32 s49, v137
	s_addc_u32 s53, s55, 0
	v_mov_b32_e32 v149, v130
	v_mov_b32_e32 v198, v1
	s_mov_b32 m0, s49
	v_readfirstlane_b32 s49, v138
	ds_read_b128 v[166:169], v148 offset:32768
	ds_read_b128 v[170:173], v148 offset:33792
	ds_read_b128 v[174:177], v148 offset:34816
	ds_read_b128 v[178:181], v148 offset:35840
	ds_read_b128 v[182:185], v148 offset:36864
	ds_read_b128 v[186:189], v148 offset:37888
	ds_read_b128 v[190:193], v148 offset:38912
	ds_read_b128 v[194:197], v148 offset:39936
	s_nop 0
	global_load_lds_dwordx4 v198, s[52:53]
	s_mov_b32 m0, s49
	s_nop 0
	global_load_lds_dwordx4 v149, s[52:53]
	s_waitcnt lgkmcnt(8)
	s_barrier
	s_waitcnt lgkmcnt(0)
	s_setprio 1
	s_waitcnt lgkmcnt(0)
	v_mfma_f32_16x16x32_bf16 v[126:129], v[150:153], v[166:169], v[126:129]
	v_mfma_f32_16x16x32_bf16 v[122:125], v[158:161], v[166:169], v[122:125]
	v_mfma_f32_16x16x32_bf16 v[110:113], v[150:153], v[174:177], v[110:113]
	v_mfma_f32_16x16x32_bf16 v[106:109], v[158:161], v[174:177], v[106:109]
	v_mfma_f32_16x16x32_bf16 v[94:97], v[150:153], v[182:185], v[94:97]
	v_mfma_f32_16x16x32_bf16 v[90:93], v[158:161], v[182:185], v[90:93]
	v_mfma_f32_16x16x32_bf16 v[78:81], v[150:153], v[190:193], v[78:81]
	v_mfma_f32_16x16x32_bf16 v[74:77], v[158:161], v[190:193], v[74:77]
	v_mfma_f32_16x16x32_bf16 v[126:129], v[154:157], v[170:173], v[126:129]
	v_mfma_f32_16x16x32_bf16 v[122:125], v[162:165], v[170:173], v[122:125]
	v_mfma_f32_16x16x32_bf16 v[110:113], v[154:157], v[178:181], v[110:113]
	v_mfma_f32_16x16x32_bf16 v[106:109], v[162:165], v[178:181], v[106:109]
	v_mfma_f32_16x16x32_bf16 v[94:97], v[154:157], v[186:189], v[94:97]
	v_mfma_f32_16x16x32_bf16 v[90:93], v[162:165], v[186:189], v[90:93]
	v_mfma_f32_16x16x32_bf16 v[78:81], v[154:157], v[194:197], v[78:81]
	v_mfma_f32_16x16x32_bf16 v[74:77], v[162:165], v[194:197], v[74:77]
	s_setprio 0
	s_barrier
	s_mov_b32 s49, s97
	s_lshl_b64 s[48:49], s[48:49], 1
	v_add_u32_e32 v149, s17, v147
	s_add_u32 s52, s10, s48
	v_readfirstlane_b32 s10, v139
	ds_read_b128 v[198:201], v149
	ds_read_b128 v[202:205], v149 offset:1024
	ds_read_b128 v[212:215], v149 offset:2048
	ds_read_b128 v[216:219], v149 offset:3072
	s_addc_u32 s53, s11, s49
	v_mov_b32_e32 v149, v130
	v_mov_b32_e32 v208, v1
	s_mov_b32 m0, s10
	v_readfirstlane_b32 s10, v140
	s_nop 0
	global_load_lds_dwordx4 v208, s[52:53]
	s_mov_b32 m0, s10
	s_nop 0
	global_load_lds_dwordx4 v149, s[52:53]
	s_barrier
; #define GM_WAIT_V(n) asm volatile("s_waitcnt vmcnt(" #n ")" ::: "memory")
; #define GM_WAIT_L(n) asm volatile("s_waitcnt lgkmcnt(" #n ")" ::: "memory")
; #define GM_BAR __builtin_amdgcn_s_barrier()
; #define GM_SCHED __builtin_amdgcn_sched_barrier(0)
; #define GM_LDA(dst, b, h) _Pragma("unroll") for (int m = 0; m < 4; ++m) _Pragma("unroll") for (int k = 0; k < 2; ++k) \
;         dst[m][k] = *(const LAS bf16x8*)(GM_SA(b, h) + aoff + (m * 2 + k) * 1024)
; #define GM_LDB(dst, b, h) _Pragma("unroll") for (int n = 0; n < 2; ++n) _Pragma("unroll") for (int k = 0; k < 2; ++k) \
;         dst[n][k] = *(const LAS bf16x8*)(GM_SB(b, h) + boff + (n * 2 + k) * 1024)
; #define GM_MMA(ai, bj, At, Bv) do { __builtin_amdgcn_s_setprio(1); \
;         _Pragma("unroll") for (int m = 0; m < 4; ++m) _Pragma("unroll") for (int n = 0; n < 2; ++n) _Pragma("unroll") for (int k = 0; k < 2; ++k) \
;             acc[ai][bj][m][n] = __builtin_amdgcn_mfma_f32_16x16x32_bf16(Bv[n][k], At[m][k], acc[ai][bj][m][n], 0, 0, 0); \
;         __builtin_amdgcn_s_setprio(0); } while (0)
; template <class Epi>
; __device__ __forceinline__ void gemm_phase(const bf16_t* __restrict__ A, const bf16_t* __restrict__ Bt, int M, int N, LAS unsigned char* lds, const Epi& epi, int vcu) {
;     ...
;             GM_WAIT_L(8); GM_BAR; GM_WAIT_L(0); GM_MMA(0, 0, At, B0); GM_BAR; GM_SCHED;
;             GM_LDB(B1, 1, 1); GM_STAGE(GM_SB(1, 0), Bt, pcol, k3);
;             GM_BAR; GM_WAIT_L(0); GM_MMA(0, 1, At, B1); GM_BAR;
;             GM_LDA(At, 1, 1); GM_STAGE(GM_SA(1, 0), A, prow, k3);
;             GM_BAR; GM_WAIT_L(0); GM_MMA(1, 0, At, B0); GM_BAR; GM_SCHED;
;             GM_STAGE(GM_SB(1, 1), Bt, pcol + HALF, k3);
;             GM_WAIT_V(6); GM_BAR; GM_MMA(1, 1, At, B1); GM_BAR;
;         }
	s_waitcnt lgkmcnt(0)
	s_setprio 1
	s_waitcnt lgkmcnt(0)
	v_mfma_f32_16x16x32_bf16 v[118:121], v[198:201], v[166:169], v[118:121]
	v_mfma_f32_16x16x32_bf16 v[114:117], v[212:215], v[166:169], v[114:117]
	v_mfma_f32_16x16x32_bf16 v[102:105], v[198:201], v[174:177], v[102:105]
	v_mfma_f32_16x16x32_bf16 v[98:101], v[212:215], v[174:177], v[98:101]
	v_mfma_f32_16x16x32_bf16 v[86:89], v[198:201], v[182:185], v[86:89]
	v_mfma_f32_16x16x32_bf16 v[82:85], v[212:215], v[182:185], v[82:85]
	v_mfma_f32_16x16x32_bf16 v[70:73], v[198:201], v[190:193], v[70:73]
	v_mfma_f32_16x16x32_bf16 v[66:69], v[212:215], v[190:193], v[66:69]
	v_mfma_f32_16x16x32_bf16 v[118:121], v[202:205], v[170:173], v[118:121]
	v_mfma_f32_16x16x32_bf16 v[114:117], v[216:219], v[170:173], v[114:117]
	v_mfma_f32_16x16x32_bf16 v[102:105], v[202:205], v[178:181], v[102:105]
	v_mfma_f32_16x16x32_bf16 v[98:101], v[216:219], v[178:181], v[98:101]
	v_mfma_f32_16x16x32_bf16 v[86:89], v[202:205], v[186:189], v[86:89]
	v_mfma_f32_16x16x32_bf16 v[82:85], v[216:219], v[186:189], v[82:85]
	v_mfma_f32_16x16x32_bf16 v[70:73], v[202:205], v[194:197], v[70:73]
	v_mfma_f32_16x16x32_bf16 v[66:69], v[216:219], v[194:197], v[66:69]
	s_setprio 0
	s_add_u32 s52, s45, s48
	v_readfirstlane_b32 s10, v141
	s_addc_u32 s53, s51, s49
	v_mov_b32_e32 v149, v130
	v_mov_b32_e32 v208, v1
	s_mov_b32 m0, s10
	v_readfirstlane_b32 s10, v142
	s_barrier
	ds_read_b128 v[166:169], v148 offset:49152
	ds_read_b128 v[170:173], v148 offset:50176
	ds_read_b128 v[174:177], v148 offset:51200
	ds_read_b128 v[178:181], v148 offset:52224
	ds_read_b128 v[182:185], v148 offset:53248
	ds_read_b128 v[186:189], v148 offset:54272
	ds_read_b128 v[190:193], v148 offset:55296
	ds_read_b128 v[194:197], v148 offset:56320
	s_nop 0
	global_load_lds_dwordx4 v208, s[52:53]
	s_mov_b32 m0, s10
	s_nop 0
	global_load_lds_dwordx4 v149, s[52:53]
	s_barrier
	s_waitcnt lgkmcnt(0)
	s_setprio 1
	s_waitcnt lgkmcnt(0)
	v_mfma_f32_16x16x32_bf16 v[62:65], v[150:153], v[166:169], v[62:65]
	v_mfma_f32_16x16x32_bf16 v[58:61], v[158:161], v[166:169], v[58:61]
	v_mfma_f32_16x16x32_bf16 v[46:49], v[150:153], v[174:177], v[46:49]
	v_mfma_f32_16x16x32_bf16 v[42:45], v[158:161], v[174:177], v[42:45]
	v_mfma_f32_16x16x32_bf16 v[30:33], v[150:153], v[182:185], v[30:33]
	v_mfma_f32_16x16x32_bf16 v[26:29], v[158:161], v[182:185], v[26:29]
	v_mfma_f32_16x16x32_bf16 v[14:17], v[150:153], v[190:193], v[14:17]
	v_mfma_f32_16x16x32_bf16 v[10:13], v[158:161], v[190:193], v[10:13]
	v_mfma_f32_16x16x32_bf16 v[62:65], v[154:157], v[170:173], v[62:65]
	v_mfma_f32_16x16x32_bf16 v[58:61], v[162:165], v[170:173], v[58:61]
	v_mfma_f32_16x16x32_bf16 v[46:49], v[154:157], v[178:181], v[46:49]
	v_mfma_f32_16x16x32_bf16 v[42:45], v[162:165], v[178:181], v[42:45]
	v_mfma_f32_16x16x32_bf16 v[30:33], v[154:157], v[186:189], v[30:33]
	v_mfma_f32_16x16x32_bf16 v[26:29], v[162:165], v[186:189], v[26:29]
	v_mfma_f32_16x16x32_bf16 v[14:17], v[154:157], v[194:197], v[14:17]
	v_mfma_f32_16x16x32_bf16 v[10:13], v[162:165], v[194:197], v[10:13]
	s_setprio 0
	s_barrier
	s_add_u32 s48, s58, s48
	v_readfirstlane_b32 s10, v143
	s_addc_u32 s49, s59, s49
	v_mov_b32_e32 v149, v130
	v_mov_b32_e32 v150, v1
	s_mov_b32 m0, s10
	v_readfirstlane_b32 s10, v144
	s_nop 0
	global_load_lds_dwordx4 v150, s[48:49]
	s_mov_b32 m0, s10
	s_nop 0
	global_load_lds_dwordx4 v149, s[48:49]
	s_waitcnt vmcnt(6)
	s_barrier
	s_setprio 1
	v_mfma_f32_16x16x32_bf16 v[54:57], v[198:201], v[166:169], v[54:57]
	v_mfma_f32_16x16x32_bf16 v[50:53], v[212:215], v[166:169], v[50:53]
	v_mfma_f32_16x16x32_bf16 v[38:41], v[198:201], v[174:177], v[38:41]
	v_mfma_f32_16x16x32_bf16 v[34:37], v[212:215], v[174:177], v[34:37]
	v_mfma_f32_16x16x32_bf16 v[22:25], v[198:201], v[182:185], v[22:25]
	v_mfma_f32_16x16x32_bf16 v[18:21], v[212:215], v[182:185], v[18:21]
	v_mfma_f32_16x16x32_bf16 v[6:9], v[198:201], v[190:193], v[6:9]
	v_mfma_f32_16x16x32_bf16 v[2:5], v[212:215], v[190:193], v[2:5]
	v_mfma_f32_16x16x32_bf16 v[54:57], v[202:205], v[170:173], v[54:57]
	v_mfma_f32_16x16x32_bf16 v[50:53], v[216:219], v[170:173], v[50:53]
	v_mfma_f32_16x16x32_bf16 v[38:41], v[202:205], v[178:181], v[38:41]
	v_mfma_f32_16x16x32_bf16 v[34:37], v[216:219], v[178:181], v[34:37]
	v_mfma_f32_16x16x32_bf16 v[22:25], v[202:205], v[186:189], v[22:25]
	v_mfma_f32_16x16x32_bf16 v[18:21], v[216:219], v[186:189], v[18:21]
	v_mfma_f32_16x16x32_bf16 v[6:9], v[202:205], v[194:197], v[6:9]
	v_mfma_f32_16x16x32_bf16 v[2:5], v[216:219], v[194:197], v[2:5]
	s_setprio 0
	s_addk_i32 s43, 0x80
	s_add_u32 s46, s46, 0x100
	s_addc_u32 s47, s47, 0
	s_barrier
	s_cbranch_vccz .LBB0_339
; #define GM_SCHED __builtin_amdgcn_sched_barrier(0)
; template <class Epi>
; __device__ __forceinline__ void gemm_phase(const bf16_t* __restrict__ A, const bf16_t* __restrict__ Bt, int M, int N, LAS unsigned char* lds, const Epi& epi, int vcu) {
;     ...
;         {
;         int fre = fr, fqe = fq; asm volatile("" : "+v"(fre), "+v"(fqe));
; #pragma unroll
;         for (int ai = 0; ai < 2; ++ai)
; #pragma unroll
;             for (int mp = 0; mp < 2; ++mp) {
; #pragma unroll
;                 for (int mq = 0; mq < 2; ++mq)
; #pragma unroll
;                     for (int bj = 0; bj < 2; ++bj) { const int m = mp * 2 + mq;
;                         epi(brow + ai * HALF + wr * 64 + m * 16 + fre, (bcol + bj * HALF + wc * 32) >> 5, fqe, acc[ai][bj][m][0], acc[ai][bj][m][1]); }
;                 GM_SCHED;
;             }
;         }
	s_add_i32 s10, s42, s4
	v_add_u32_e32 v149, s10, v145
	s_or_b32 s11, s44, s5
	v_lshl_add_u32 v212, v146, 3, s11
	s_lshr_b32 s2, s42, 13
	s_mul_i32 s2, s2, 0x3000
	s_add_u32 s10, s26, s2
	s_addc_u32 s11, s27, 0
	v_lshlrev_b32_e32 v213, 2, v212
	global_load_dwordx4 v[150:153], v213, s[10:11]
	global_load_dwordx4 v[154:157], v213, s[10:11] offset:16
	global_load_dwordx4 v[158:161], v213, s[10:11] offset:512
	global_load_dwordx4 v[162:165], v213, s[10:11] offset:528
	v_lshl_add_u32 v149, v149, 10, v212
	v_lshlrev_b32_e32 v149, 2, v149
	s_mov_b64 s[46:47], s[14:15]
	s_mov_b64 s[10:11], s[62:63]
	global_load_dwordx4 v[166:169], v149, s[46:47]
	global_load_dwordx4 v[170:173], v149, s[46:47] offset:16
	global_load_dwordx4 v[174:177], v149, s[46:47] offset:512
	global_load_dwordx4 v[178:181], v149, s[46:47] offset:528
	s_add_u32 s46, s46, 0x10000
	s_addc_u32 s47, s47, 0
	global_load_dwordx4 v[182:185], v149, s[46:47]
	global_load_dwordx4 v[186:189], v149, s[46:47] offset:16
	global_load_dwordx4 v[190:193], v149, s[46:47] offset:512
	global_load_dwordx4 v[194:197], v149, s[46:47] offset:528
	s_add_u32 s46, s46, 0x10000
	s_addc_u32 s47, s47, 0
	global_load_dwordx4 v[198:201], v149, s[46:47]
	global_load_dwordx4 v[202:205], v149, s[46:47] offset:16
	global_load_dwordx4 v[212:215], v149, s[46:47] offset:512
	global_load_dwordx4 v[216:219], v149, s[46:47] offset:528
	s_add_u32 s46, s46, 0x10000
	s_addc_u32 s47, s47, 0
	s_waitcnt vmcnt(10)
	v_pk_fma_f32 v[126:127], v[126:127], v[150:151], v[166:167]
	v_pk_fma_f32 v[128:129], v[128:129], v[152:153], v[168:169]
	v_pk_fma_f32 v[122:123], v[122:123], v[154:155], v[170:171]
	v_pk_fma_f32 v[124:125], v[124:125], v[156:157], v[172:173]
	global_store_dwordx4 v149, v[126:129], s[10:11]
	global_store_dwordx4 v149, v[122:125], s[10:11] offset:16
	global_load_dwordx4 v[166:169], v149, s[46:47]
	global_load_dwordx4 v[170:173], v149, s[46:47] offset:16
	s_waitcnt vmcnt(12)
	v_pk_fma_f32 v[118:119], v[118:119], v[158:159], v[174:175]
	v_pk_fma_f32 v[120:121], v[120:121], v[160:161], v[176:177]
	v_pk_fma_f32 v[114:115], v[114:115], v[162:163], v[178:179]
	v_pk_fma_f32 v[116:117], v[116:117], v[164:165], v[180:181]
	global_store_dwordx4 v149, v[118:121], s[10:11] offset:512
	global_store_dwordx4 v149, v[114:117], s[10:11] offset:528
	s_add_u32 s10, s10, 0x10000
	s_addc_u32 s11, s11, 0
	global_load_dwordx4 v[174:177], v149, s[46:47] offset:512
	global_load_dwordx4 v[178:181], v149, s[46:47] offset:528
	s_add_u32 s46, s46, 0x50000
	s_addc_u32 s47, s47, 0
	s_waitcnt vmcnt(14)
	v_pk_fma_f32 v[110:111], v[110:111], v[150:151], v[182:183]
	v_pk_fma_f32 v[112:113], v[112:113], v[152:153], v[184:185]
	v_pk_fma_f32 v[106:107], v[106:107], v[154:155], v[186:187]
	v_pk_fma_f32 v[108:109], v[108:109], v[156:157], v[188:189]
	global_store_dwordx4 v149, v[110:113], s[10:11]
	global_store_dwordx4 v149, v[106:109], s[10:11] offset:16
	global_load_dwordx4 v[182:185], v149, s[46:47]
	global_load_dwordx4 v[186:189], v149, s[46:47] offset:16
	s_waitcnt vmcnt(16)
	v_pk_fma_f32 v[102:103], v[102:103], v[158:159], v[190:191]
	v_pk_fma_f32 v[104:105], v[104:105], v[160:161], v[192:193]
	v_pk_fma_f32 v[98:99], v[98:99], v[162:163], v[194:195]
	v_pk_fma_f32 v[100:101], v[100:101], v[164:165], v[196:197]
	global_store_dwordx4 v149, v[102:105], s[10:11] offset:512
	global_store_dwordx4 v149, v[98:101], s[10:11] offset:528
	s_add_u32 s10, s10, 0x10000
	s_addc_u32 s11, s11, 0
	global_load_dwordx4 v[190:193], v149, s[46:47] offset:512
	global_load_dwordx4 v[194:197], v149, s[46:47] offset:528
	s_add_u32 s46, s46, 0x10000
	s_addc_u32 s47, s47, 0
	s_waitcnt vmcnt(18)
	v_pk_fma_f32 v[94:95], v[94:95], v[150:151], v[198:199]
	v_pk_fma_f32 v[96:97], v[96:97], v[152:153], v[200:201]
	v_pk_fma_f32 v[90:91], v[90:91], v[154:155], v[202:203]
	v_pk_fma_f32 v[92:93], v[92:93], v[156:157], v[204:205]
	global_store_dwordx4 v149, v[94:97], s[10:11]
	global_store_dwordx4 v149, v[90:93], s[10:11] offset:16
	global_load_dwordx4 v[198:201], v149, s[46:47]
	global_load_dwordx4 v[202:205], v149, s[46:47] offset:16
	s_waitcnt vmcnt(20)
	v_pk_fma_f32 v[86:87], v[86:87], v[158:159], v[212:213]
	v_pk_fma_f32 v[88:89], v[88:89], v[160:161], v[214:215]
	v_pk_fma_f32 v[82:83], v[82:83], v[162:163], v[216:217]
	v_pk_fma_f32 v[84:85], v[84:85], v[164:165], v[218:219]
	global_store_dwordx4 v149, v[86:89], s[10:11] offset:512
	global_store_dwordx4 v149, v[82:85], s[10:11] offset:528
	s_add_u32 s10, s10, 0x10000
	s_addc_u32 s11, s11, 0
	global_load_dwordx4 v[212:215], v149, s[46:47] offset:512
	global_load_dwordx4 v[216:219], v149, s[46:47] offset:528
	s_add_u32 s46, s46, 0x10000
	s_addc_u32 s47, s47, 0
	s_waitcnt vmcnt(20)
; #define GM_WAIT_V(n) asm volatile("s_waitcnt vmcnt(" #n ")" ::: "memory")
; #define GM_BAR __builtin_amdgcn_s_barrier()
; template <class Epi>
; __device__ __forceinline__ void gemm_phase(const bf16_t* __restrict__ A, const bf16_t* __restrict__ Bt, int M, int N, LAS unsigned char* lds, const Epi& epi, int vcu) {
;     ...
;         if (!have_next) break;
;         brow = nrow; bcol = ncol;
;     }
;     GM_WAIT_V(0);
;     if (wr == 0) GM_BAR;
	v_pk_fma_f32 v[78:79], v[78:79], v[150:151], v[166:167]
	v_pk_fma_f32 v[80:81], v[80:81], v[152:153], v[168:169]
	v_pk_fma_f32 v[74:75], v[74:75], v[154:155], v[170:171]
	v_pk_fma_f32 v[76:77], v[76:77], v[156:157], v[172:173]
	global_store_dwordx4 v149, v[78:81], s[10:11]
	global_store_dwordx4 v149, v[74:77], s[10:11] offset:16
	global_load_dwordx4 v[166:169], v149, s[46:47]
	global_load_dwordx4 v[170:173], v149, s[46:47] offset:16
	s_waitcnt vmcnt(20)
	v_pk_fma_f32 v[70:71], v[70:71], v[158:159], v[174:175]
	v_pk_fma_f32 v[72:73], v[72:73], v[160:161], v[176:177]
	v_pk_fma_f32 v[66:67], v[66:67], v[162:163], v[178:179]
	v_pk_fma_f32 v[68:69], v[68:69], v[164:165], v[180:181]
	global_store_dwordx4 v149, v[70:73], s[10:11] offset:512
	global_store_dwordx4 v149, v[66:69], s[10:11] offset:528
	s_add_u32 s10, s10, 0x50000
	s_addc_u32 s11, s11, 0
	global_load_dwordx4 v[174:177], v149, s[46:47] offset:512
	global_load_dwordx4 v[178:181], v149, s[46:47] offset:528
	s_add_u32 s46, s46, 0x10000
	s_addc_u32 s47, s47, 0
	s_waitcnt vmcnt(20)
	v_pk_fma_f32 v[62:63], v[62:63], v[150:151], v[182:183]
	v_pk_fma_f32 v[64:65], v[64:65], v[152:153], v[184:185]
	v_pk_fma_f32 v[58:59], v[58:59], v[154:155], v[186:187]
	v_pk_fma_f32 v[60:61], v[60:61], v[156:157], v[188:189]
	global_store_dwordx4 v149, v[62:65], s[10:11]
	global_store_dwordx4 v149, v[58:61], s[10:11] offset:16
	global_load_dwordx4 v[182:185], v149, s[46:47]
	global_load_dwordx4 v[186:189], v149, s[46:47] offset:16
	s_waitcnt vmcnt(20)
	v_pk_fma_f32 v[54:55], v[54:55], v[158:159], v[190:191]
	v_pk_fma_f32 v[56:57], v[56:57], v[160:161], v[192:193]
	v_pk_fma_f32 v[50:51], v[50:51], v[162:163], v[194:195]
	v_pk_fma_f32 v[52:53], v[52:53], v[164:165], v[196:197]
	global_store_dwordx4 v149, v[54:57], s[10:11] offset:512
	global_store_dwordx4 v149, v[50:53], s[10:11] offset:528
	s_add_u32 s10, s10, 0x10000
	s_addc_u32 s11, s11, 0
	global_load_dwordx4 v[190:193], v149, s[46:47] offset:512
	global_load_dwordx4 v[194:197], v149, s[46:47] offset:528
	s_waitcnt vmcnt(20)
	v_pk_fma_f32 v[46:47], v[46:47], v[150:151], v[198:199]
	v_pk_fma_f32 v[48:49], v[48:49], v[152:153], v[200:201]
	v_pk_fma_f32 v[42:43], v[42:43], v[154:155], v[202:203]
	v_pk_fma_f32 v[44:45], v[44:45], v[156:157], v[204:205]
	global_store_dwordx4 v149, v[46:49], s[10:11]
	global_store_dwordx4 v149, v[42:45], s[10:11] offset:16
	s_waitcnt vmcnt(18)
	v_pk_fma_f32 v[38:39], v[38:39], v[158:159], v[212:213]
	v_pk_fma_f32 v[40:41], v[40:41], v[160:161], v[214:215]
	v_pk_fma_f32 v[34:35], v[34:35], v[162:163], v[216:217]
	v_pk_fma_f32 v[36:37], v[36:37], v[164:165], v[218:219]
	global_store_dwordx4 v149, v[38:41], s[10:11] offset:512
	global_store_dwordx4 v149, v[34:37], s[10:11] offset:528
	s_add_u32 s10, s10, 0x10000
	s_addc_u32 s11, s11, 0
	s_waitcnt vmcnt(16)
	v_pk_fma_f32 v[30:31], v[30:31], v[150:151], v[166:167]
	v_pk_fma_f32 v[32:33], v[32:33], v[152:153], v[168:169]
	v_pk_fma_f32 v[26:27], v[26:27], v[154:155], v[170:171]
	v_pk_fma_f32 v[28:29], v[28:29], v[156:157], v[172:173]
	global_store_dwordx4 v149, v[30:33], s[10:11]
	global_store_dwordx4 v149, v[26:29], s[10:11] offset:16
	s_waitcnt vmcnt(14)
	v_pk_fma_f32 v[22:23], v[22:23], v[158:159], v[174:175]
	v_pk_fma_f32 v[24:25], v[24:25], v[160:161], v[176:177]
	v_pk_fma_f32 v[18:19], v[18:19], v[162:163], v[178:179]
	v_pk_fma_f32 v[20:21], v[20:21], v[164:165], v[180:181]
	global_store_dwordx4 v149, v[22:25], s[10:11] offset:512
	global_store_dwordx4 v149, v[18:21], s[10:11] offset:528
	s_add_u32 s10, s10, 0x10000
	s_addc_u32 s11, s11, 0
	s_waitcnt vmcnt(12)
	v_pk_fma_f32 v[14:15], v[14:15], v[150:151], v[182:183]
	v_pk_fma_f32 v[16:17], v[16:17], v[152:153], v[184:185]
	v_pk_fma_f32 v[10:11], v[10:11], v[154:155], v[186:187]
	v_pk_fma_f32 v[12:13], v[12:13], v[156:157], v[188:189]
	global_store_dwordx4 v149, v[14:17], s[10:11]
	global_store_dwordx4 v149, v[10:13], s[10:11] offset:16
	s_waitcnt vmcnt(10)
	v_pk_fma_f32 v[6:7], v[6:7], v[158:159], v[190:191]
	v_pk_fma_f32 v[8:9], v[8:9], v[160:161], v[192:193]
	v_pk_fma_f32 v[2:3], v[2:3], v[162:163], v[194:195]
	v_pk_fma_f32 v[4:5], v[4:5], v[164:165], v[196:197]
	global_store_dwordx4 v149, v[6:9], s[10:11] offset:512
	global_store_dwordx4 v149, v[2:5], s[10:11] offset:528
	v_readlane_b32 s58, v255, 16
	s_and_b64 vcc, exec, s[40:41]
	s_mov_b32 s42, s29
	s_mov_b32 s44, s28
	v_readlane_b32 s59, v255, 17
	v_readlane_b32 s64, v255, 18
	s_mov_b32 s65, 0xf800000
	s_cbranch_vccz .LBB0_332
	s_waitcnt vmcnt(0)
	s_cmpk_gt_u32 s21, 0xff
	s_cbranch_scc1 .LBB0_343
	s_barrier
